# attention work queue: the fetch-add for the next unit issued before the store drain and barrier at the loop top (overlaps its round trip)
# speedup vs baseline: 1.0038x; 1.0038x over previous
; DI int lane_id_() { unsigned m = ~0u; asm volatile("" : "+s"(m)); return (int)__builtin_amdgcn_mbcnt_hi(m, __builtin_amdgcn_mbcnt_lo(m, 0u)); }
; __global__ void __launch_bounds__(512, 2) mega(Params p) {
;     ...
;             for (;;) {
;                 __syncthreads();
;                 if (wv == 0 && lane_id_() == 0) *unext = (int)__hip_atomic_fetch_add(ctr, 1u, __ATOMIC_RELAXED, __HIP_MEMORY_SCOPE_AGENT);
;                 __syncthreads();
.LBB0_507:
	s_and_b64 vcc, exec, s[62:63]
	s_cbranch_vccnz .Ldeal_sync
	s_mov_b32 s0, -1
	v_mbcnt_lo_u32_b32 v0, s0, 0
	v_mbcnt_hi_u32_b32 v0, s0, v0
	v_cmp_eq_u32_e32 vcc, 0, v0
	s_and_saveexec_b64 s[0:1], vcc
	s_cbranch_execz .Ldeal_issued
	v_readlane_b32 s2, v255, 1
	v_readlane_b32 s3, v255, 2
	s_nop 1
	v_mov_b64_e32 v[0:1], s[2:3]
	flat_atomic_add v0, v[0:1], v200 sc0

; DI int lane_id_() { unsigned m = ~0u; asm volatile("" : "+s"(m)); return (int)__builtin_amdgcn_mbcnt_hi(m, __builtin_amdgcn_mbcnt_lo(m, 0u)); }
; __global__ void __launch_bounds__(512, 2) mega(Params p) {
;     ...
;                 __syncthreads();
;                 if (wv == 0 && lane_id_() == 0) *unext = (int)__hip_atomic_fetch_add(ctr, 1u, __ATOMIC_RELAXED, __HIP_MEMORY_SCOPE_AGENT);
;                 __syncthreads();
;                 const int u = *unext;
.Ldeal_sync:
	s_waitcnt vmcnt(0) lgkmcnt(0)
	s_barrier
	s_and_b64 vcc, exec, s[62:63]
	s_cbranch_vccnz .LBB0_511
	s_mov_b32 s0, -1
	v_mbcnt_lo_u32_b32 v1, s0, 0
	v_mbcnt_hi_u32_b32 v1, s0, v1
	v_cmp_eq_u32_e32 vcc, 0, v1
	s_and_saveexec_b64 s[0:1], vcc
	s_cbranch_execz .LBB0_510
	v_mov_b32_e32 v1, s4
	s_nop 0
	ds_write_b32 v1, v0
